# LayerNorm tail rows (split-K partial sums): all partial loads issued up front in LN1 and LN2 instead of one round trip per load
# speedup vs baseline: 1.0955x; 1.0087x over previous
.LBB0_932:
	s_andn2_saveexec_b64 s[4:5], s[4:5]
	s_cbranch_execz .LBB0_937
	v_add_u32_e32 v172, 0xffffc000, v60
	v_lshlrev_b64 v[56:57], 11, v[172:173]
	v_lshl_add_u64 v[56:57], v[22:23], 0, v[56:57]
	v_readlane_b32 s18, v253, 34
	v_readlane_b32 s19, v253, 35
	s_mov_b64 vcc, 0x80000
	v_lshl_add_u64 v[60:61], v[56:57], 0, vcc
	global_load_dwordx2 v[116:117], v[60:61], off
	global_load_dwordx2 v[118:119], v[60:61], off offset:512
	global_load_dwordx2 v[120:121], v[60:61], off offset:1024
	global_load_dwordx2 v[122:123], v[60:61], off offset:1536
	s_mov_b64 vcc, 0x100000
	v_lshl_add_u64 v[60:61], v[56:57], 0, vcc
	global_load_dwordx2 v[124:125], v[60:61], off
	global_load_dwordx2 v[126:127], v[60:61], off offset:512
	global_load_dwordx2 v[128:129], v[60:61], off offset:1024
	global_load_dwordx2 v[130:131], v[60:61], off offset:1536
	s_mov_b64 vcc, 0x180000
	v_lshl_add_u64 v[60:61], v[56:57], 0, vcc
	global_load_dwordx2 v[132:133], v[60:61], off
	global_load_dwordx2 v[134:135], v[60:61], off offset:512
	global_load_dwordx2 v[136:137], v[60:61], off offset:1024
	global_load_dwordx2 v[138:139], v[60:61], off offset:1536
	s_and_b64 vcc, exec, s[18:19]
	s_cbranch_vccz .Lln1_tail_b
	s_mov_b64 vcc, 0x200000
	v_lshl_add_u64 v[60:61], v[56:57], 0, vcc
	global_load_dwordx2 v[204:205], v[60:61], off
	global_load_dwordx2 v[206:207], v[60:61], off offset:512
	global_load_dwordx2 v[208:209], v[60:61], off offset:1024
	global_load_dwordx2 v[210:211], v[60:61], off offset:1536
	s_mov_b64 vcc, 0x280000
	v_lshl_add_u64 v[60:61], v[56:57], 0, vcc
	global_load_dwordx2 v[212:213], v[60:61], off
	global_load_dwordx2 v[214:215], v[60:61], off offset:512
	global_load_dwordx2 v[216:217], v[60:61], off offset:1024
	global_load_dwordx2 v[218:219], v[60:61], off offset:1536
	s_waitcnt vmcnt(19)
	v_lshlrev_b32_e32 v68, 16, v116
	v_and_b32_e32 v69, 0xffff0000, v116
	v_lshlrev_b32_e32 v70, 16, v117
	v_and_b32_e32 v71, 0xffff0000, v117
	v_pk_add_f32 v[48:49], v[48:49], v[68:69]
	v_pk_add_f32 v[46:47], v[46:47], v[70:71]
	s_waitcnt vmcnt(18)
	v_lshlrev_b32_e32 v68, 16, v118
	v_and_b32_e32 v69, 0xffff0000, v118
	v_lshlrev_b32_e32 v70, 16, v119
	v_and_b32_e32 v71, 0xffff0000, v119
	v_pk_add_f32 v[52:53], v[52:53], v[68:69]
	v_pk_add_f32 v[58:59], v[58:59], v[70:71]
	s_waitcnt vmcnt(17)
	v_lshlrev_b32_e32 v68, 16, v120
	v_and_b32_e32 v69, 0xffff0000, v120
	v_lshlrev_b32_e32 v70, 16, v121
	v_and_b32_e32 v71, 0xffff0000, v121
	v_pk_add_f32 v[42:43], v[42:43], v[68:69]
	v_pk_add_f32 v[54:55], v[54:55], v[70:71]
	s_waitcnt vmcnt(16)
	v_lshlrev_b32_e32 v68, 16, v122
	v_and_b32_e32 v69, 0xffff0000, v122
	v_lshlrev_b32_e32 v70, 16, v123
	v_and_b32_e32 v71, 0xffff0000, v123
	v_pk_add_f32 v[50:51], v[50:51], v[68:69]
	v_pk_add_f32 v[44:45], v[44:45], v[70:71]
	s_waitcnt vmcnt(15)
	v_lshlrev_b32_e32 v68, 16, v124
	v_and_b32_e32 v69, 0xffff0000, v124
	v_lshlrev_b32_e32 v70, 16, v125
	v_and_b32_e32 v71, 0xffff0000, v125
	v_pk_add_f32 v[48:49], v[48:49], v[68:69]
	v_pk_add_f32 v[46:47], v[46:47], v[70:71]
	s_waitcnt vmcnt(14)
	v_lshlrev_b32_e32 v68, 16, v126
	v_and_b32_e32 v69, 0xffff0000, v126
	v_lshlrev_b32_e32 v70, 16, v127
	v_and_b32_e32 v71, 0xffff0000, v127
	v_pk_add_f32 v[52:53], v[52:53], v[68:69]
	v_pk_add_f32 v[58:59], v[58:59], v[70:71]
	s_waitcnt vmcnt(13)
	v_lshlrev_b32_e32 v68, 16, v128
	v_and_b32_e32 v69, 0xffff0000, v128
	v_lshlrev_b32_e32 v70, 16, v129
	v_and_b32_e32 v71, 0xffff0000, v129
	v_pk_add_f32 v[42:43], v[42:43], v[68:69]
	v_pk_add_f32 v[54:55], v[54:55], v[70:71]
	s_waitcnt vmcnt(12)
	v_lshlrev_b32_e32 v68, 16, v130
	v_and_b32_e32 v69, 0xffff0000, v130
	v_lshlrev_b32_e32 v70, 16, v131
	v_and_b32_e32 v71, 0xffff0000, v131
	v_pk_add_f32 v[50:51], v[50:51], v[68:69]
	v_pk_add_f32 v[44:45], v[44:45], v[70:71]
	s_waitcnt vmcnt(11)
	v_lshlrev_b32_e32 v68, 16, v132
	v_and_b32_e32 v69, 0xffff0000, v132
	v_lshlrev_b32_e32 v70, 16, v133
	v_and_b32_e32 v71, 0xffff0000, v133
	v_pk_add_f32 v[48:49], v[48:49], v[68:69]
	v_pk_add_f32 v[46:47], v[46:47], v[70:71]
	s_waitcnt vmcnt(10)
	v_lshlrev_b32_e32 v68, 16, v134
	v_and_b32_e32 v69, 0xffff0000, v134
	v_lshlrev_b32_e32 v70, 16, v135
	v_and_b32_e32 v71, 0xffff0000, v135
	v_pk_add_f32 v[52:53], v[52:53], v[68:69]
	v_pk_add_f32 v[58:59], v[58:59], v[70:71]
	s_waitcnt vmcnt(9)
	v_lshlrev_b32_e32 v68, 16, v136
	v_and_b32_e32 v69, 0xffff0000, v136
	v_lshlrev_b32_e32 v70, 16, v137
	v_and_b32_e32 v71, 0xffff0000, v137
	v_pk_add_f32 v[42:43], v[42:43], v[68:69]
	v_pk_add_f32 v[54:55], v[54:55], v[70:71]
	s_waitcnt vmcnt(8)
	v_lshlrev_b32_e32 v68, 16, v138
	v_and_b32_e32 v69, 0xffff0000, v138
	v_lshlrev_b32_e32 v70, 16, v139
	v_and_b32_e32 v71, 0xffff0000, v139
	v_pk_add_f32 v[50:51], v[50:51], v[68:69]
	v_pk_add_f32 v[44:45], v[44:45], v[70:71]
	s_waitcnt vmcnt(7)
	v_lshlrev_b32_e32 v68, 16, v204
	v_and_b32_e32 v69, 0xffff0000, v204
	v_lshlrev_b32_e32 v70, 16, v205
	v_and_b32_e32 v71, 0xffff0000, v205
	v_pk_add_f32 v[48:49], v[48:49], v[68:69]
	v_pk_add_f32 v[46:47], v[46:47], v[70:71]
	s_waitcnt vmcnt(6)
	v_lshlrev_b32_e32 v68, 16, v206
	v_and_b32_e32 v69, 0xffff0000, v206
	v_lshlrev_b32_e32 v70, 16, v207
	v_and_b32_e32 v71, 0xffff0000, v207
	v_pk_add_f32 v[52:53], v[52:53], v[68:69]
	v_pk_add_f32 v[58:59], v[58:59], v[70:71]
	s_waitcnt vmcnt(5)
	v_lshlrev_b32_e32 v68, 16, v208
	v_and_b32_e32 v69, 0xffff0000, v208
	v_lshlrev_b32_e32 v70, 16, v209
	v_and_b32_e32 v71, 0xffff0000, v209
	v_pk_add_f32 v[42:43], v[42:43], v[68:69]
	v_pk_add_f32 v[54:55], v[54:55], v[70:71]
	s_waitcnt vmcnt(4)
	v_lshlrev_b32_e32 v68, 16, v210
	v_and_b32_e32 v69, 0xffff0000, v210
	v_lshlrev_b32_e32 v70, 16, v211
	v_and_b32_e32 v71, 0xffff0000, v211
	v_pk_add_f32 v[50:51], v[50:51], v[68:69]
	v_pk_add_f32 v[44:45], v[44:45], v[70:71]
	s_waitcnt vmcnt(3)
	v_lshlrev_b32_e32 v68, 16, v212
	v_and_b32_e32 v69, 0xffff0000, v212
	v_lshlrev_b32_e32 v70, 16, v213
	v_and_b32_e32 v71, 0xffff0000, v213
	v_pk_add_f32 v[48:49], v[48:49], v[68:69]
	v_pk_add_f32 v[46:47], v[46:47], v[70:71]
	s_waitcnt vmcnt(2)
	v_lshlrev_b32_e32 v68, 16, v214
	v_and_b32_e32 v69, 0xffff0000, v214
	v_lshlrev_b32_e32 v70, 16, v215
	v_and_b32_e32 v71, 0xffff0000, v215
	v_pk_add_f32 v[52:53], v[52:53], v[68:69]
	v_pk_add_f32 v[58:59], v[58:59], v[70:71]
	s_waitcnt vmcnt(1)
	v_lshlrev_b32_e32 v68, 16, v216
	v_and_b32_e32 v69, 0xffff0000, v216
	v_lshlrev_b32_e32 v70, 16, v217
	v_and_b32_e32 v71, 0xffff0000, v217
	v_pk_add_f32 v[42:43], v[42:43], v[68:69]
	v_pk_add_f32 v[54:55], v[54:55], v[70:71]
	s_waitcnt vmcnt(0)
	v_lshlrev_b32_e32 v68, 16, v218
	v_and_b32_e32 v69, 0xffff0000, v218
	v_lshlrev_b32_e32 v70, 16, v219
	v_and_b32_e32 v71, 0xffff0000, v219
	v_pk_add_f32 v[50:51], v[50:51], v[68:69]
	v_pk_add_f32 v[44:45], v[44:45], v[70:71]
	s_branch .Lln1_tail_done
.Lln1_tail_b:
	s_waitcnt vmcnt(11)
	v_lshlrev_b32_e32 v68, 16, v116
	v_and_b32_e32 v69, 0xffff0000, v116
	v_lshlrev_b32_e32 v70, 16, v117
	v_and_b32_e32 v71, 0xffff0000, v117
	v_pk_add_f32 v[48:49], v[48:49], v[68:69]
	v_pk_add_f32 v[46:47], v[46:47], v[70:71]
	s_waitcnt vmcnt(10)
	v_lshlrev_b32_e32 v68, 16, v118
	v_and_b32_e32 v69, 0xffff0000, v118
	v_lshlrev_b32_e32 v70, 16, v119
	v_and_b32_e32 v71, 0xffff0000, v119
	v_pk_add_f32 v[52:53], v[52:53], v[68:69]
	v_pk_add_f32 v[58:59], v[58:59], v[70:71]
	s_waitcnt vmcnt(9)
	v_lshlrev_b32_e32 v68, 16, v120
	v_and_b32_e32 v69, 0xffff0000, v120
	v_lshlrev_b32_e32 v70, 16, v121
	v_and_b32_e32 v71, 0xffff0000, v121
	v_pk_add_f32 v[42:43], v[42:43], v[68:69]
	v_pk_add_f32 v[54:55], v[54:55], v[70:71]
	s_waitcnt vmcnt(8)
	v_lshlrev_b32_e32 v68, 16, v122
	v_and_b32_e32 v69, 0xffff0000, v122
	v_lshlrev_b32_e32 v70, 16, v123
	v_and_b32_e32 v71, 0xffff0000, v123
	v_pk_add_f32 v[50:51], v[50:51], v[68:69]
	v_pk_add_f32 v[44:45], v[44:45], v[70:71]
	s_waitcnt vmcnt(7)
	v_lshlrev_b32_e32 v68, 16, v124
	v_and_b32_e32 v69, 0xffff0000, v124
	v_lshlrev_b32_e32 v70, 16, v125
	v_and_b32_e32 v71, 0xffff0000, v125
	v_pk_add_f32 v[48:49], v[48:49], v[68:69]
	v_pk_add_f32 v[46:47], v[46:47], v[70:71]
	s_waitcnt vmcnt(6)
	v_lshlrev_b32_e32 v68, 16, v126
	v_and_b32_e32 v69, 0xffff0000, v126
	v_lshlrev_b32_e32 v70, 16, v127
	v_and_b32_e32 v71, 0xffff0000, v127
	v_pk_add_f32 v[52:53], v[52:53], v[68:69]
	v_pk_add_f32 v[58:59], v[58:59], v[70:71]
	s_waitcnt vmcnt(5)
	v_lshlrev_b32_e32 v68, 16, v128
	v_and_b32_e32 v69, 0xffff0000, v128
	v_lshlrev_b32_e32 v70, 16, v129
	v_and_b32_e32 v71, 0xffff0000, v129
	v_pk_add_f32 v[42:43], v[42:43], v[68:69]
	v_pk_add_f32 v[54:55], v[54:55], v[70:71]
	s_waitcnt vmcnt(4)
	v_lshlrev_b32_e32 v68, 16, v130
	v_and_b32_e32 v69, 0xffff0000, v130
	v_lshlrev_b32_e32 v70, 16, v131
	v_and_b32_e32 v71, 0xffff0000, v131
	v_pk_add_f32 v[50:51], v[50:51], v[68:69]
	v_pk_add_f32 v[44:45], v[44:45], v[70:71]
	s_waitcnt vmcnt(3)
	v_lshlrev_b32_e32 v68, 16, v132
	v_and_b32_e32 v69, 0xffff0000, v132
	v_lshlrev_b32_e32 v70, 16, v133
	v_and_b32_e32 v71, 0xffff0000, v133
	v_pk_add_f32 v[48:49], v[48:49], v[68:69]
	v_pk_add_f32 v[46:47], v[46:47], v[70:71]
	s_waitcnt vmcnt(2)
	v_lshlrev_b32_e32 v68, 16, v134
	v_and_b32_e32 v69, 0xffff0000, v134
	v_lshlrev_b32_e32 v70, 16, v135
	v_and_b32_e32 v71, 0xffff0000, v135
	v_pk_add_f32 v[52:53], v[52:53], v[68:69]
	v_pk_add_f32 v[58:59], v[58:59], v[70:71]
	s_waitcnt vmcnt(1)
	v_lshlrev_b32_e32 v68, 16, v136
	v_and_b32_e32 v69, 0xffff0000, v136
	v_lshlrev_b32_e32 v70, 16, v137
	v_and_b32_e32 v71, 0xffff0000, v137
	v_pk_add_f32 v[42:43], v[42:43], v[68:69]
	v_pk_add_f32 v[54:55], v[54:55], v[70:71]
	s_waitcnt vmcnt(0)
	v_lshlrev_b32_e32 v68, 16, v138
	v_and_b32_e32 v69, 0xffff0000, v138
	v_lshlrev_b32_e32 v70, 16, v139
	v_and_b32_e32 v71, 0xffff0000, v139
	v_pk_add_f32 v[50:51], v[50:51], v[68:69]
	v_pk_add_f32 v[44:45], v[44:45], v[70:71]
.Lln1_tail_done:
	v_mov_b32_e32 v62, v52
	v_mov_b32_e32 v63, v53
	v_mov_b32_e32 v60, v58
	v_mov_b32_e32 v61, v59
	v_mov_b32_e32 v66, v42
	v_mov_b32_e32 v67, v43
	v_mov_b32_e32 v64, v54
	v_mov_b32_e32 v65, v55

.LBB0_1112:
	s_waitcnt vmcnt(8)
	v_lshlrev_b32_e32 v2, 16, v8
	v_and_b32_e32 v3, 0xffff0000, v8
	s_waitcnt vmcnt(4)
	v_lshlrev_b32_e32 v62, 16, v18
	v_and_b32_e32 v63, 0xffff0000, v18
	v_lshlrev_b32_e32 v60, 16, v9
	v_and_b32_e32 v61, 0xffff0000, v9
	v_lshlrev_b32_e32 v64, 16, v19
	v_and_b32_e32 v65, 0xffff0000, v19
	v_pk_add_f32 v[2:3], v[2:3], v[62:63]
	v_lshlrev_b32_e32 v62, 16, v4
	v_and_b32_e32 v63, 0xffff0000, v4
	v_pk_add_f32 v[60:61], v[60:61], v[64:65]
	v_lshlrev_b32_e32 v64, 16, v5
	v_and_b32_e32 v65, 0xffff0000, v5
	v_pk_add_f32 v[62:63], v[62:63], 0 op_sel_hi:[1,0]
	v_pk_add_f32 v[64:65], v[64:65], 0 op_sel_hi:[1,0]
	v_pk_fma_f32 v[2:3], v[2:3], s[80:81], v[62:63] op_sel_hi:[1,0,1]
	v_pk_fma_f32 v[74:75], v[60:61], s[80:81], v[64:65] op_sel_hi:[1,0,1]
	v_pk_mul_f32 v[64:65], v[2:3], v[2:3]
	v_pk_mul_f32 v[62:63], v[74:75], v[74:75]
	v_fmac_f32_e32 v65, v2, v2
	v_add_f32_e32 v76, v62, v65
	v_lshlrev_b32_e32 v62, 16, v10
	v_and_b32_e32 v63, 0xffff0000, v10
	s_waitcnt vmcnt(3)
	v_lshlrev_b32_e32 v66, 16, v20
	v_and_b32_e32 v67, 0xffff0000, v20
	v_pk_add_f32 v[62:63], v[62:63], v[66:67]
	v_lshlrev_b32_e32 v66, 16, v6
	v_and_b32_e32 v67, 0xffff0000, v6
	v_lshlrev_b32_e32 v64, 16, v11
	v_and_b32_e32 v65, 0xffff0000, v11
	v_lshlrev_b32_e32 v68, 16, v21
	v_and_b32_e32 v69, 0xffff0000, v21
	v_pk_add_f32 v[66:67], v[66:67], 0 op_sel_hi:[1,0]
	v_add_f32_e32 v1, v2, v3
	v_pk_add_f32 v[64:65], v[64:65], v[68:69]
	v_lshlrev_b32_e32 v68, 16, v7
	v_and_b32_e32 v69, 0xffff0000, v7
	v_pk_fma_f32 v[70:71], v[62:63], s[80:81], v[66:67] op_sel_hi:[1,0,1]
	v_add_f32_e32 v61, v74, v1
	v_pk_add_f32 v[68:69], v[68:69], 0 op_sel_hi:[1,0]
	v_mul_f32_e32 v60, v71, v71
	v_pk_fma_f32 v[72:73], v[64:65], s[80:81], v[68:69] op_sel_hi:[1,0,1]
	v_pk_fma_f32 v[62:63], v[70:71], v[70:71], v[60:61] op_sel_hi:[1,1,0]
	v_mul_f32_e32 v60, v73, v73
	v_pk_fma_f32 v[62:63], v[72:73], v[72:73], v[62:63]
	s_waitcnt vmcnt(2)
	v_lshlrev_b32_e32 v66, 16, v22
	v_pk_add_f32 v[82:83], v[60:61], v[62:63] op_sel_hi:[0,1]
	v_lshlrev_b32_e32 v62, 16, v12
	v_and_b32_e32 v63, 0xffff0000, v12
	v_and_b32_e32 v67, 0xffff0000, v22
	v_pk_add_f32 v[62:63], v[62:63], v[66:67]
	v_lshlrev_b32_e32 v66, 16, v16
	v_and_b32_e32 v67, 0xffff0000, v16
	v_lshlrev_b32_e32 v64, 16, v13
	v_and_b32_e32 v65, 0xffff0000, v13
	v_lshlrev_b32_e32 v68, 16, v23
	v_and_b32_e32 v69, 0xffff0000, v23
	v_pk_add_f32 v[66:67], v[66:67], 0 op_sel_hi:[1,0]
	v_pk_add_f32 v[64:65], v[64:65], v[68:69]
	v_lshlrev_b32_e32 v68, 16, v17
	v_and_b32_e32 v69, 0xffff0000, v17
	v_pk_fma_f32 v[66:67], v[62:63], s[80:81], v[66:67] op_sel_hi:[1,0,1]
	v_pk_add_f32 v[68:69], v[68:69], 0 op_sel_hi:[1,0]
	v_mul_f32_e32 v60, v67, v67
	v_pk_fma_f32 v[68:69], v[64:65], s[80:81], v[68:69] op_sel_hi:[1,0,1]
	v_pk_fma_f32 v[62:63], v[66:67], v[66:67], v[60:61] op_sel_hi:[1,1,0]
	v_mul_f32_e32 v60, v69, v69
	v_pk_fma_f32 v[62:63], v[68:69], v[68:69], v[62:63]
	s_waitcnt vmcnt(1)
	v_lshlrev_b32_e32 v94, 16, v24
	v_pk_add_f32 v[92:93], v[60:61], v[62:63] op_sel_hi:[0,1]
	v_lshlrev_b32_e32 v62, 16, v14
	v_and_b32_e32 v63, 0xffff0000, v14
	v_and_b32_e32 v95, 0xffff0000, v24
	v_lshlrev_b32_e32 v64, 16, v15
	v_and_b32_e32 v65, 0xffff0000, v15
	v_lshlrev_b32_e32 v96, 16, v25
	v_and_b32_e32 v97, 0xffff0000, v25
	v_pk_add_f32 v[62:63], v[62:63], v[94:95]
	s_waitcnt vmcnt(0)
	v_lshlrev_b32_e32 v94, 16, v26
	v_and_b32_e32 v95, 0xffff0000, v26
	v_add_f32_e32 v1, v70, v71
	v_pk_add_f32 v[64:65], v[64:65], v[96:97]
	v_lshlrev_b32_e32 v96, 16, v27
	v_and_b32_e32 v97, 0xffff0000, v27
	v_pk_add_f32 v[94:95], v[94:95], 0 op_sel_hi:[1,0]
	v_add_f32_e32 v1, v72, v1
	v_pk_add_f32 v[96:97], v[96:97], 0 op_sel_hi:[1,0]
	v_pk_fma_f32 v[62:63], v[62:63], s[80:81], v[94:95] op_sel_hi:[1,0,1]
	v_mul_f32_e32 v78, v75, v75
	v_add_f32_e32 v81, v73, v1
	v_add_f32_e32 v1, v66, v67
	v_pk_fma_f32 v[64:65], v[64:65], s[80:81], v[96:97] op_sel_hi:[1,0,1]
	v_mul_f32_e32 v94, v62, v62
	v_mul_f32_e32 v60, v63, v63
	v_mov_b32_e32 v79, v62
	v_mov_b32_e32 v77, v63
	v_mov_b32_e32 v95, v75
	v_add_f32_e32 v1, v68, v1
	v_mul_f32_e32 v80, v64, v64
	v_pk_add_f32 v[76:77], v[78:79], v[76:77]
	v_mov_b32_e32 v83, v64
	v_pk_add_f32 v[60:61], v[94:95], v[60:61]
	v_add_f32_e32 v85, v69, v1
	v_mul_f32_e32 v84, v65, v65
	v_pk_add_f32 v[76:77], v[82:83], v[76:77]
	v_mov_b32_e32 v93, v65
	v_pk_add_f32 v[60:61], v[80:81], v[60:61]
	v_pk_add_f32 v[76:77], v[92:93], v[76:77]
	v_pk_add_f32 v[60:61], v[84:85], v[60:61]
	s_movk_i32 s0, 0x3fff
	v_pk_add_f32 v[76:77], v[76:77], v[60:61]
	v_cmp_lt_i32_e32 vcc, s0, v0
	s_and_saveexec_b64 s[6:7], vcc
	s_cbranch_execz .LBB0_1116
	v_mov_b32_e32 v53, v173
	v_lshlrev_b64 v[60:61], 11, v[52:53]
	v_lshl_add_u64 v[60:61], v[50:51], 0, v[60:61]
	s_mov_b64 s[8:9], 0
	s_mov_b64 s[8:9], 0x15279000
	v_lshl_add_u64 v[78:79], v[60:61], 0, s[8:9]
	global_load_dwordx2 v[114:115], v[78:79], off
	global_load_dwordx2 v[116:117], v[78:79], off offset:512
	global_load_dwordx2 v[118:119], v[78:79], off offset:1024
	global_load_dwordx2 v[120:121], v[78:79], off offset:1536
	s_mov_b64 s[8:9], 0x152f9000
	v_lshl_add_u64 v[78:79], v[60:61], 0, s[8:9]
	global_load_dwordx2 v[122:123], v[78:79], off
	global_load_dwordx2 v[124:125], v[78:79], off offset:512
	global_load_dwordx2 v[126:127], v[78:79], off offset:1024
	global_load_dwordx2 v[128:129], v[78:79], off offset:1536
	s_mov_b64 s[8:9], 0x15379000
	v_lshl_add_u64 v[78:79], v[60:61], 0, s[8:9]
	global_load_dwordx2 v[130:131], v[78:79], off
	global_load_dwordx2 v[132:133], v[78:79], off offset:512
	global_load_dwordx2 v[134:135], v[78:79], off offset:1024
	global_load_dwordx2 v[136:137], v[78:79], off offset:1536
	s_mov_b64 s[8:9], 0x153f9000
	v_lshl_add_u64 v[78:79], v[60:61], 0, s[8:9]
	global_load_dwordx2 v[138:139], v[78:79], off
	global_load_dwordx2 v[204:205], v[78:79], off offset:512
	global_load_dwordx2 v[206:207], v[78:79], off offset:1024
	global_load_dwordx2 v[208:209], v[78:79], off offset:1536
	s_mov_b64 s[8:9], 0x15479000
	v_lshl_add_u64 v[78:79], v[60:61], 0, s[8:9]
	global_load_dwordx2 v[210:211], v[78:79], off
	global_load_dwordx2 v[212:213], v[78:79], off offset:512
	global_load_dwordx2 v[214:215], v[78:79], off offset:1024
	global_load_dwordx2 v[216:217], v[78:79], off offset:1536
	s_mov_b64 s[8:9], 0x154f9000
	v_lshl_add_u64 v[78:79], v[60:61], 0, s[8:9]
	global_load_dwordx2 v[218:219], v[78:79], off
	global_load_dwordx2 v[220:221], v[78:79], off offset:512
	global_load_dwordx2 v[222:223], v[78:79], off offset:1024
	global_load_dwordx2 v[224:225], v[78:79], off offset:1536
	s_mov_b64 s[8:9], 0x15579000
	v_lshl_add_u64 v[78:79], v[60:61], 0, s[8:9]
	global_load_dwordx2 v[226:227], v[78:79], off
	global_load_dwordx2 v[228:229], v[78:79], off offset:512
	global_load_dwordx2 v[230:231], v[78:79], off offset:1024
	global_load_dwordx2 v[232:233], v[78:79], off offset:1536
	s_mov_b64 s[8:9], 0x155f9000
	v_lshl_add_u64 v[78:79], v[60:61], 0, s[8:9]
	global_load_dwordx2 v[234:235], v[78:79], off
	global_load_dwordx2 v[236:237], v[78:79], off offset:512
	global_load_dwordx2 v[238:239], v[78:79], off offset:1024
	global_load_dwordx2 v[240:241], v[78:79], off offset:1536
	s_mov_b64 s[8:9], 0x15679000
	v_lshl_add_u64 v[78:79], v[60:61], 0, s[8:9]
	global_load_dwordx2 v[242:243], v[78:79], off
	global_load_dwordx2 v[244:245], v[78:79], off offset:512
	global_load_dwordx2 v[246:247], v[78:79], off offset:1024
	global_load_dwordx2 v[248:249], v[78:79], off offset:1536
	s_mov_b64 s[8:9], 0x156f9000
	v_lshl_add_u64 v[78:79], v[60:61], 0, s[8:9]
	global_load_dwordx2 v[250:251], v[78:79], off
	global_load_dwordx2 v[174:175], v[78:79], off offset:512
	global_load_dwordx2 v[176:177], v[78:79], off offset:1024
	global_load_dwordx2 v[180:181], v[78:79], off offset:1536
	s_waitcnt vmcnt(39)
	v_lshlrev_b32_e32 v80, 16, v114
	v_and_b32_e32 v81, 0xffff0000, v114
	v_lshlrev_b32_e32 v82, 16, v115
	v_and_b32_e32 v83, 0xffff0000, v115
	v_pk_add_f32 v[2:3], v[2:3], v[80:81]
	v_pk_add_f32 v[74:75], v[74:75], v[82:83]
	s_waitcnt vmcnt(38)
	v_lshlrev_b32_e32 v80, 16, v116
	v_and_b32_e32 v81, 0xffff0000, v116
	v_lshlrev_b32_e32 v82, 16, v117
	v_and_b32_e32 v83, 0xffff0000, v117
	v_pk_add_f32 v[70:71], v[70:71], v[80:81]
	v_pk_add_f32 v[72:73], v[72:73], v[82:83]
	s_waitcnt vmcnt(37)
	v_lshlrev_b32_e32 v80, 16, v118
	v_and_b32_e32 v81, 0xffff0000, v118
	v_lshlrev_b32_e32 v82, 16, v119
	v_and_b32_e32 v83, 0xffff0000, v119
	v_pk_add_f32 v[66:67], v[66:67], v[80:81]
	v_pk_add_f32 v[68:69], v[68:69], v[82:83]
	s_waitcnt vmcnt(36)
	v_lshlrev_b32_e32 v80, 16, v120
	v_and_b32_e32 v81, 0xffff0000, v120
	v_lshlrev_b32_e32 v82, 16, v121
	v_and_b32_e32 v83, 0xffff0000, v121
	v_pk_add_f32 v[62:63], v[62:63], v[80:81]
	v_pk_add_f32 v[64:65], v[64:65], v[82:83]
	s_waitcnt vmcnt(35)
	v_lshlrev_b32_e32 v80, 16, v122
	v_and_b32_e32 v81, 0xffff0000, v122
	v_lshlrev_b32_e32 v82, 16, v123
	v_and_b32_e32 v83, 0xffff0000, v123
	v_pk_add_f32 v[2:3], v[2:3], v[80:81]
	v_pk_add_f32 v[74:75], v[74:75], v[82:83]
	s_waitcnt vmcnt(34)
	v_lshlrev_b32_e32 v80, 16, v124
	v_and_b32_e32 v81, 0xffff0000, v124
	v_lshlrev_b32_e32 v82, 16, v125
	v_and_b32_e32 v83, 0xffff0000, v125
	v_pk_add_f32 v[70:71], v[70:71], v[80:81]
	v_pk_add_f32 v[72:73], v[72:73], v[82:83]
	s_waitcnt vmcnt(33)
	v_lshlrev_b32_e32 v80, 16, v126
	v_and_b32_e32 v81, 0xffff0000, v126
	v_lshlrev_b32_e32 v82, 16, v127
	v_and_b32_e32 v83, 0xffff0000, v127
	v_pk_add_f32 v[66:67], v[66:67], v[80:81]
	v_pk_add_f32 v[68:69], v[68:69], v[82:83]
	s_waitcnt vmcnt(32)
	v_lshlrev_b32_e32 v80, 16, v128
	v_and_b32_e32 v81, 0xffff0000, v128
	v_lshlrev_b32_e32 v82, 16, v129
	v_and_b32_e32 v83, 0xffff0000, v129
	v_pk_add_f32 v[62:63], v[62:63], v[80:81]
	v_pk_add_f32 v[64:65], v[64:65], v[82:83]
	s_waitcnt vmcnt(31)
	v_lshlrev_b32_e32 v80, 16, v130
	v_and_b32_e32 v81, 0xffff0000, v130
	v_lshlrev_b32_e32 v82, 16, v131
	v_and_b32_e32 v83, 0xffff0000, v131
	v_pk_add_f32 v[2:3], v[2:3], v[80:81]
	v_pk_add_f32 v[74:75], v[74:75], v[82:83]
	s_waitcnt vmcnt(30)
	v_lshlrev_b32_e32 v80, 16, v132
	v_and_b32_e32 v81, 0xffff0000, v132
	v_lshlrev_b32_e32 v82, 16, v133
	v_and_b32_e32 v83, 0xffff0000, v133
	v_pk_add_f32 v[70:71], v[70:71], v[80:81]
	v_pk_add_f32 v[72:73], v[72:73], v[82:83]
	s_waitcnt vmcnt(29)
	v_lshlrev_b32_e32 v80, 16, v134
	v_and_b32_e32 v81, 0xffff0000, v134
	v_lshlrev_b32_e32 v82, 16, v135
	v_and_b32_e32 v83, 0xffff0000, v135
	v_pk_add_f32 v[66:67], v[66:67], v[80:81]
	v_pk_add_f32 v[68:69], v[68:69], v[82:83]
	s_waitcnt vmcnt(28)
	v_lshlrev_b32_e32 v80, 16, v136
	v_and_b32_e32 v81, 0xffff0000, v136
	v_lshlrev_b32_e32 v82, 16, v137
	v_and_b32_e32 v83, 0xffff0000, v137
	v_pk_add_f32 v[62:63], v[62:63], v[80:81]
	v_pk_add_f32 v[64:65], v[64:65], v[82:83]
	s_waitcnt vmcnt(27)
	v_lshlrev_b32_e32 v80, 16, v138
	v_and_b32_e32 v81, 0xffff0000, v138
	v_lshlrev_b32_e32 v82, 16, v139
	v_and_b32_e32 v83, 0xffff0000, v139
	v_pk_add_f32 v[2:3], v[2:3], v[80:81]
	v_pk_add_f32 v[74:75], v[74:75], v[82:83]
	s_waitcnt vmcnt(26)
	v_lshlrev_b32_e32 v80, 16, v204
	v_and_b32_e32 v81, 0xffff0000, v204
	v_lshlrev_b32_e32 v82, 16, v205
	v_and_b32_e32 v83, 0xffff0000, v205
	v_pk_add_f32 v[70:71], v[70:71], v[80:81]
	v_pk_add_f32 v[72:73], v[72:73], v[82:83]
	s_waitcnt vmcnt(25)
	v_lshlrev_b32_e32 v80, 16, v206
	v_and_b32_e32 v81, 0xffff0000, v206
	v_lshlrev_b32_e32 v82, 16, v207
	v_and_b32_e32 v83, 0xffff0000, v207
	v_pk_add_f32 v[66:67], v[66:67], v[80:81]
	v_pk_add_f32 v[68:69], v[68:69], v[82:83]
	s_waitcnt vmcnt(24)
	v_lshlrev_b32_e32 v80, 16, v208
	v_and_b32_e32 v81, 0xffff0000, v208
	v_lshlrev_b32_e32 v82, 16, v209
	v_and_b32_e32 v83, 0xffff0000, v209
	v_pk_add_f32 v[62:63], v[62:63], v[80:81]
	v_pk_add_f32 v[64:65], v[64:65], v[82:83]
	s_waitcnt vmcnt(23)
	v_lshlrev_b32_e32 v80, 16, v210
	v_and_b32_e32 v81, 0xffff0000, v210
	v_lshlrev_b32_e32 v82, 16, v211
	v_and_b32_e32 v83, 0xffff0000, v211
	v_pk_add_f32 v[2:3], v[2:3], v[80:81]
	v_pk_add_f32 v[74:75], v[74:75], v[82:83]
	s_waitcnt vmcnt(22)
	v_lshlrev_b32_e32 v80, 16, v212
	v_and_b32_e32 v81, 0xffff0000, v212
	v_lshlrev_b32_e32 v82, 16, v213
	v_and_b32_e32 v83, 0xffff0000, v213
	v_pk_add_f32 v[70:71], v[70:71], v[80:81]
	v_pk_add_f32 v[72:73], v[72:73], v[82:83]
	s_waitcnt vmcnt(21)
	v_lshlrev_b32_e32 v80, 16, v214
	v_and_b32_e32 v81, 0xffff0000, v214
	v_lshlrev_b32_e32 v82, 16, v215
	v_and_b32_e32 v83, 0xffff0000, v215
	v_pk_add_f32 v[66:67], v[66:67], v[80:81]
	v_pk_add_f32 v[68:69], v[68:69], v[82:83]
	s_waitcnt vmcnt(20)
	v_lshlrev_b32_e32 v80, 16, v216
	v_and_b32_e32 v81, 0xffff0000, v216
	v_lshlrev_b32_e32 v82, 16, v217
	v_and_b32_e32 v83, 0xffff0000, v217
	v_pk_add_f32 v[62:63], v[62:63], v[80:81]
	v_pk_add_f32 v[64:65], v[64:65], v[82:83]
	s_waitcnt vmcnt(19)
	v_lshlrev_b32_e32 v80, 16, v218
	v_and_b32_e32 v81, 0xffff0000, v218
	v_lshlrev_b32_e32 v82, 16, v219
	v_and_b32_e32 v83, 0xffff0000, v219
	v_pk_add_f32 v[2:3], v[2:3], v[80:81]
	v_pk_add_f32 v[74:75], v[74:75], v[82:83]
	s_waitcnt vmcnt(18)
	v_lshlrev_b32_e32 v80, 16, v220
	v_and_b32_e32 v81, 0xffff0000, v220
	v_lshlrev_b32_e32 v82, 16, v221
	v_and_b32_e32 v83, 0xffff0000, v221
	v_pk_add_f32 v[70:71], v[70:71], v[80:81]
	v_pk_add_f32 v[72:73], v[72:73], v[82:83]
	s_waitcnt vmcnt(17)
	v_lshlrev_b32_e32 v80, 16, v222
	v_and_b32_e32 v81, 0xffff0000, v222
	v_lshlrev_b32_e32 v82, 16, v223
	v_and_b32_e32 v83, 0xffff0000, v223
	v_pk_add_f32 v[66:67], v[66:67], v[80:81]
	v_pk_add_f32 v[68:69], v[68:69], v[82:83]
	s_waitcnt vmcnt(16)
	v_lshlrev_b32_e32 v80, 16, v224
	v_and_b32_e32 v81, 0xffff0000, v224
	v_lshlrev_b32_e32 v82, 16, v225
	v_and_b32_e32 v83, 0xffff0000, v225
	v_pk_add_f32 v[62:63], v[62:63], v[80:81]
	v_pk_add_f32 v[64:65], v[64:65], v[82:83]
	s_waitcnt vmcnt(15)
	v_lshlrev_b32_e32 v80, 16, v226
	v_and_b32_e32 v81, 0xffff0000, v226
	v_lshlrev_b32_e32 v82, 16, v227
	v_and_b32_e32 v83, 0xffff0000, v227
	v_pk_add_f32 v[2:3], v[2:3], v[80:81]
	v_pk_add_f32 v[74:75], v[74:75], v[82:83]
	s_waitcnt vmcnt(14)
	v_lshlrev_b32_e32 v80, 16, v228
	v_and_b32_e32 v81, 0xffff0000, v228
	v_lshlrev_b32_e32 v82, 16, v229
	v_and_b32_e32 v83, 0xffff0000, v229
	v_pk_add_f32 v[70:71], v[70:71], v[80:81]
	v_pk_add_f32 v[72:73], v[72:73], v[82:83]
	s_waitcnt vmcnt(13)
	v_lshlrev_b32_e32 v80, 16, v230
	v_and_b32_e32 v81, 0xffff0000, v230
	v_lshlrev_b32_e32 v82, 16, v231
	v_and_b32_e32 v83, 0xffff0000, v231
	v_pk_add_f32 v[66:67], v[66:67], v[80:81]
	v_pk_add_f32 v[68:69], v[68:69], v[82:83]
	s_waitcnt vmcnt(12)
	v_lshlrev_b32_e32 v80, 16, v232
	v_and_b32_e32 v81, 0xffff0000, v232
	v_lshlrev_b32_e32 v82, 16, v233
	v_and_b32_e32 v83, 0xffff0000, v233
	v_pk_add_f32 v[62:63], v[62:63], v[80:81]
	v_pk_add_f32 v[64:65], v[64:65], v[82:83]
	s_waitcnt vmcnt(11)
	v_lshlrev_b32_e32 v80, 16, v234
	v_and_b32_e32 v81, 0xffff0000, v234
	v_lshlrev_b32_e32 v82, 16, v235
	v_and_b32_e32 v83, 0xffff0000, v235
	v_pk_add_f32 v[2:3], v[2:3], v[80:81]
	v_pk_add_f32 v[74:75], v[74:75], v[82:83]
	s_waitcnt vmcnt(10)
	v_lshlrev_b32_e32 v80, 16, v236
	v_and_b32_e32 v81, 0xffff0000, v236
	v_lshlrev_b32_e32 v82, 16, v237
	v_and_b32_e32 v83, 0xffff0000, v237
	v_pk_add_f32 v[70:71], v[70:71], v[80:81]
	v_pk_add_f32 v[72:73], v[72:73], v[82:83]
	s_waitcnt vmcnt(9)
	v_lshlrev_b32_e32 v80, 16, v238
	v_and_b32_e32 v81, 0xffff0000, v238
	v_lshlrev_b32_e32 v82, 16, v239
	v_and_b32_e32 v83, 0xffff0000, v239
	v_pk_add_f32 v[66:67], v[66:67], v[80:81]
	v_pk_add_f32 v[68:69], v[68:69], v[82:83]
	s_waitcnt vmcnt(8)
	v_lshlrev_b32_e32 v80, 16, v240
	v_and_b32_e32 v81, 0xffff0000, v240
	v_lshlrev_b32_e32 v82, 16, v241
	v_and_b32_e32 v83, 0xffff0000, v241
	v_pk_add_f32 v[62:63], v[62:63], v[80:81]
	v_pk_add_f32 v[64:65], v[64:65], v[82:83]
	s_waitcnt vmcnt(7)
	v_lshlrev_b32_e32 v80, 16, v242
	v_and_b32_e32 v81, 0xffff0000, v242
	v_lshlrev_b32_e32 v82, 16, v243
	v_and_b32_e32 v83, 0xffff0000, v243
	v_pk_add_f32 v[2:3], v[2:3], v[80:81]
	v_pk_add_f32 v[74:75], v[74:75], v[82:83]
	s_waitcnt vmcnt(6)
	v_lshlrev_b32_e32 v80, 16, v244
	v_and_b32_e32 v81, 0xffff0000, v244
	v_lshlrev_b32_e32 v82, 16, v245
	v_and_b32_e32 v83, 0xffff0000, v245
	v_pk_add_f32 v[70:71], v[70:71], v[80:81]
	v_pk_add_f32 v[72:73], v[72:73], v[82:83]
	s_waitcnt vmcnt(5)
	v_lshlrev_b32_e32 v80, 16, v246
	v_and_b32_e32 v81, 0xffff0000, v246
	v_lshlrev_b32_e32 v82, 16, v247
	v_and_b32_e32 v83, 0xffff0000, v247
	v_pk_add_f32 v[66:67], v[66:67], v[80:81]
	v_pk_add_f32 v[68:69], v[68:69], v[82:83]
	s_waitcnt vmcnt(4)
	v_lshlrev_b32_e32 v80, 16, v248
	v_and_b32_e32 v81, 0xffff0000, v248
	v_lshlrev_b32_e32 v82, 16, v249
	v_and_b32_e32 v83, 0xffff0000, v249
	v_pk_add_f32 v[62:63], v[62:63], v[80:81]
	v_pk_add_f32 v[64:65], v[64:65], v[82:83]
	s_waitcnt vmcnt(3)
	v_lshlrev_b32_e32 v80, 16, v250
	v_and_b32_e32 v81, 0xffff0000, v250
	v_lshlrev_b32_e32 v82, 16, v251
	v_and_b32_e32 v83, 0xffff0000, v251
	v_pk_add_f32 v[2:3], v[2:3], v[80:81]
	v_pk_add_f32 v[74:75], v[74:75], v[82:83]
	s_waitcnt vmcnt(2)
	v_lshlrev_b32_e32 v80, 16, v174
	v_and_b32_e32 v81, 0xffff0000, v174
	v_lshlrev_b32_e32 v82, 16, v175
	v_and_b32_e32 v83, 0xffff0000, v175
	v_pk_add_f32 v[70:71], v[70:71], v[80:81]
	v_pk_add_f32 v[72:73], v[72:73], v[82:83]
	s_waitcnt vmcnt(1)
	v_lshlrev_b32_e32 v80, 16, v176
	v_and_b32_e32 v81, 0xffff0000, v176
	v_lshlrev_b32_e32 v82, 16, v177
	v_and_b32_e32 v83, 0xffff0000, v177
	v_pk_add_f32 v[66:67], v[66:67], v[80:81]
	v_pk_add_f32 v[68:69], v[68:69], v[82:83]
	s_waitcnt vmcnt(0)
	v_lshlrev_b32_e32 v80, 16, v180
	v_and_b32_e32 v81, 0xffff0000, v180
	v_lshlrev_b32_e32 v82, 16, v181
	v_and_b32_e32 v83, 0xffff0000, v181
	v_pk_add_f32 v[62:63], v[62:63], v[80:81]
	v_pk_add_f32 v[64:65], v[64:65], v[82:83]
	v_pk_mul_f32 v[78:79], v[2:3], v[2:3]
	v_pk_add_f32 v[80:81], v[2:3], v[2:3] op_sel_hi:[0,1]
	v_mul_f32_e32 v60, v3, v3
	v_mov_b32_e32 v79, v81
	v_mov_b32_e32 v61, v74
	v_pk_mul_f32 v[80:81], v[70:71], v[70:71]
	v_mul_f32_e32 v76, v74, v74
	v_pk_add_f32 v[60:61], v[60:61], v[78:79]
	v_mov_b32_e32 v77, v75
	v_add_f32_e32 v1, v70, v71
	v_pk_mul_f32 v[78:79], v[72:73], v[72:73]
	v_fmac_f32_e32 v81, v70, v70
	v_pk_mul_f32 v[84:85], v[66:67], v[66:67]
	v_pk_add_f32 v[60:61], v[76:77], v[60:61]
	v_mul_f32_e32 v172, v75, v75
	v_add_f32_e32 v77, v72, v1
	v_add_f32_e32 v78, v78, v81
	v_mul_f32_e32 v76, v73, v73
	v_add_f32_e32 v1, v66, v67
	v_pk_mul_f32 v[82:83], v[68:69], v[68:69]
	v_fmac_f32_e32 v85, v66, v66
	v_pk_mul_f32 v[94:95], v[62:63], v[62:63]
	v_mov_b32_e32 v79, v73
	v_add_f32_e32 v81, v68, v1
	v_add_f32_e32 v82, v82, v85
	v_mul_f32_e32 v80, v69, v69
	v_add_f32_e32 v1, v62, v63
	v_pk_mul_f32 v[92:93], v[64:65], v[64:65]
	v_fmac_f32_e32 v95, v62, v62
	v_pk_add_f32 v[60:61], v[60:61], v[172:173]
	v_pk_add_f32 v[76:77], v[78:79], v[76:77]
	v_mov_b32_e32 v83, v69
	v_add_f32_e32 v85, v64, v1
	v_add_f32_e32 v92, v92, v95
	v_mul_f32_e32 v84, v65, v65
	v_pk_add_f32 v[60:61], v[60:61], v[76:77]
	v_pk_add_f32 v[76:77], v[82:83], v[80:81]
	v_mov_b32_e32 v93, v65
	v_pk_add_f32 v[60:61], v[60:61], v[76:77]
	v_pk_add_f32 v[76:77], v[92:93], v[84:85]
	s_nop 0
	v_pk_add_f32 v[76:77], v[60:61], v[76:77]
